# GEMM K-loops: removed the redundant mid-block s_setprio 0/1 pair (two issue slots per 32-MFMA block)
# speedup vs baseline: 1.0142x; 1.0028x over previous
.LBB0_135:
	s_add_u32 s6, s52, 0xfffc0080
	s_addc_u32 s7, s53, -1
	s_add_i32 s24, 0, 0x10000
	s_cmp_eq_u32 s72, 12
	s_cselect_b32 s57, s47, s7
	s_cselect_b32 s56, s68, s6
	v_add_u32_e32 v148, s24, v151
	s_cselect_b32 s55, s45, s71
	s_cselect_b32 s54, s69, s70
	s_add_i32 s25, 0, 0x14000
	ds_read_b128 v[140:143], v148
	ds_read_b128 v[144:147], v148 offset:1024
	ds_read_b128 v[156:159], v148 offset:2048
	ds_read_b128 v[160:163], v148 offset:3072
	v_add_u32_e32 v148, s25, v151
	ds_read_b128 v[164:167], v148
	ds_read_b128 v[168:171], v148 offset:1024
	ds_read_b128 v[172:175], v148 offset:2048
	ds_read_b128 v[176:179], v148 offset:3072
	v_lshl_add_u64 v[148:149], s[52:53], 0, v[136:137]
	s_add_i32 m0, s61, 0xc000
	ds_read_b128 v[180:183], v154
	ds_read_b128 v[184:187], v154 offset:1024
	ds_read_b128 v[188:191], v154 offset:2048
	ds_read_b128 v[192:195], v154 offset:3072
	ds_read_b128 v[196:199], v154 offset:4096
	ds_read_b128 v[200:203], v154 offset:5120
	ds_read_b128 v[204:207], v154 offset:6144
	ds_read_b128 v[208:211], v154 offset:7168
	global_load_lds_dwordx4 v[148:149], off
	v_lshl_add_u64 v[148:149], s[52:53], 0, v[138:139]
	s_add_i32 m0, s61, 0xe000
	s_nop 0
	global_load_lds_dwordx4 v[148:149], off
	s_waitcnt vmcnt(8)
	s_waitcnt lgkmcnt(0)
	s_barrier
	s_setprio 1
	s_waitcnt lgkmcnt(0)
	v_mfma_f32_16x16x32_bf16 v[126:129], v[140:143], v[180:183], v[126:129]
	v_mfma_f32_16x16x32_bf16 v[122:125], v[156:159], v[180:183], v[122:125]
	v_mfma_f32_16x16x32_bf16 v[110:113], v[140:143], v[188:191], v[110:113]
	v_mfma_f32_16x16x32_bf16 v[106:109], v[156:159], v[188:191], v[106:109]
	v_mfma_f32_16x16x32_bf16 v[94:97], v[140:143], v[196:199], v[94:97]
	v_mfma_f32_16x16x32_bf16 v[90:93], v[156:159], v[196:199], v[90:93]
	v_mfma_f32_16x16x32_bf16 v[78:81], v[140:143], v[204:207], v[78:81]
	v_mfma_f32_16x16x32_bf16 v[74:77], v[156:159], v[204:207], v[74:77]
	v_mfma_f32_16x16x32_bf16 v[126:129], v[144:147], v[184:187], v[126:129]
	v_mfma_f32_16x16x32_bf16 v[122:125], v[160:163], v[184:187], v[122:125]
	v_mfma_f32_16x16x32_bf16 v[110:113], v[144:147], v[192:195], v[110:113]
	v_mfma_f32_16x16x32_bf16 v[106:109], v[160:163], v[192:195], v[106:109]
	v_mfma_f32_16x16x32_bf16 v[94:97], v[144:147], v[200:203], v[94:97]
	v_mfma_f32_16x16x32_bf16 v[90:93], v[160:163], v[200:203], v[90:93]
	v_mfma_f32_16x16x32_bf16 v[78:81], v[144:147], v[208:211], v[78:81]
	v_mfma_f32_16x16x32_bf16 v[74:77], v[160:163], v[208:211], v[74:77]
	v_mfma_f32_16x16x32_bf16 v[118:121], v[164:167], v[180:183], v[118:121]
	v_mfma_f32_16x16x32_bf16 v[114:117], v[172:175], v[180:183], v[114:117]
	v_mfma_f32_16x16x32_bf16 v[102:105], v[164:167], v[188:191], v[102:105]
	v_mfma_f32_16x16x32_bf16 v[98:101], v[172:175], v[188:191], v[98:101]
	v_mfma_f32_16x16x32_bf16 v[86:89], v[164:167], v[196:199], v[86:89]
	v_mfma_f32_16x16x32_bf16 v[82:85], v[172:175], v[196:199], v[82:85]
	v_mfma_f32_16x16x32_bf16 v[70:73], v[164:167], v[204:207], v[70:73]
	v_mfma_f32_16x16x32_bf16 v[66:69], v[172:175], v[204:207], v[66:69]
	v_mfma_f32_16x16x32_bf16 v[118:121], v[168:171], v[184:187], v[118:121]
	v_mfma_f32_16x16x32_bf16 v[114:117], v[176:179], v[184:187], v[114:117]
	v_mfma_f32_16x16x32_bf16 v[102:105], v[168:171], v[192:195], v[102:105]
	v_mfma_f32_16x16x32_bf16 v[98:101], v[176:179], v[192:195], v[98:101]
	v_mfma_f32_16x16x32_bf16 v[86:89], v[168:171], v[200:203], v[86:89]
	v_mfma_f32_16x16x32_bf16 v[82:85], v[176:179], v[200:203], v[82:85]
	v_mfma_f32_16x16x32_bf16 v[70:73], v[168:171], v[208:211], v[70:73]
	v_mfma_f32_16x16x32_bf16 v[66:69], v[176:179], v[208:211], v[66:69]
	s_setprio 0
	s_barrier
	s_add_i32 s6, s24, s60
	v_lshl_add_u64 v[148:149], s[54:55], 0, v[0:1]
	s_mov_b32 m0, s6
	ds_read_b128 v[180:183], v154 offset:16384
	ds_read_b128 v[184:187], v154 offset:17408
	ds_read_b128 v[188:191], v154 offset:18432
	ds_read_b128 v[192:195], v154 offset:19456
	ds_read_b128 v[196:199], v154 offset:20480
	ds_read_b128 v[200:203], v154 offset:21504
	ds_read_b128 v[204:207], v154 offset:22528
	ds_read_b128 v[208:211], v154 offset:23552
	global_load_lds_dwordx4 v[148:149], off
	s_add_i32 m0, s6, 0x2000
	s_add_u32 s6, s54, 0x40000
	v_lshl_add_u64 v[212:213], s[54:55], 0, v[130:131]
	s_addc_u32 s7, s55, 0
	s_add_i32 s24, s25, s60
	global_load_lds_dwordx4 v[212:213], off
	v_lshl_add_u64 v[214:215], s[6:7], 0, v[0:1]
	s_mov_b32 m0, s24
	v_lshl_add_u64 v[216:217], s[56:57], 0, v[132:133]
	global_load_lds_dwordx4 v[214:215], off
	v_lshl_add_u64 v[214:215], s[6:7], 0, v[130:131]
	s_add_i32 m0, s24, 0x2000
	s_nop 0
	global_load_lds_dwordx4 v[214:215], off
	v_lshl_add_u64 v[214:215], s[56:57], 0, v[134:135]
	s_mov_b32 m0, s61
	s_nop 0
	global_load_lds_dwordx4 v[214:215], off
	s_mov_b32 m0, s62
	s_nop 0
	global_load_lds_dwordx4 v[216:217], off
	s_waitcnt vmcnt(8)
	s_waitcnt lgkmcnt(0)
	s_barrier
	s_setprio 1
	s_waitcnt lgkmcnt(0)
	v_mfma_f32_16x16x32_bf16 v[62:65], v[140:143], v[180:183], v[62:65]
	v_mfma_f32_16x16x32_bf16 v[58:61], v[156:159], v[180:183], v[58:61]
	v_mfma_f32_16x16x32_bf16 v[46:49], v[140:143], v[188:191], v[46:49]
	v_mfma_f32_16x16x32_bf16 v[42:45], v[156:159], v[188:191], v[42:45]
	v_mfma_f32_16x16x32_bf16 v[30:33], v[140:143], v[196:199], v[30:33]
	v_mfma_f32_16x16x32_bf16 v[26:29], v[156:159], v[196:199], v[26:29]
	v_mfma_f32_16x16x32_bf16 v[14:17], v[140:143], v[204:207], v[14:17]
	v_mfma_f32_16x16x32_bf16 v[10:13], v[156:159], v[204:207], v[10:13]
	v_mfma_f32_16x16x32_bf16 v[62:65], v[144:147], v[184:187], v[62:65]
	v_mfma_f32_16x16x32_bf16 v[58:61], v[160:163], v[184:187], v[58:61]
	v_mfma_f32_16x16x32_bf16 v[46:49], v[144:147], v[192:195], v[46:49]
	v_mfma_f32_16x16x32_bf16 v[42:45], v[160:163], v[192:195], v[42:45]
	v_mfma_f32_16x16x32_bf16 v[30:33], v[144:147], v[200:203], v[30:33]
	v_mfma_f32_16x16x32_bf16 v[26:29], v[160:163], v[200:203], v[26:29]
	v_mfma_f32_16x16x32_bf16 v[14:17], v[144:147], v[208:211], v[14:17]
	v_mfma_f32_16x16x32_bf16 v[10:13], v[160:163], v[208:211], v[10:13]
	v_mfma_f32_16x16x32_bf16 v[54:57], v[164:167], v[180:183], v[54:57]
	v_mfma_f32_16x16x32_bf16 v[50:53], v[172:175], v[180:183], v[50:53]
	v_mfma_f32_16x16x32_bf16 v[38:41], v[164:167], v[188:191], v[38:41]
	v_mfma_f32_16x16x32_bf16 v[34:37], v[172:175], v[188:191], v[34:37]
	v_mfma_f32_16x16x32_bf16 v[22:25], v[164:167], v[196:199], v[22:25]
	v_mfma_f32_16x16x32_bf16 v[18:21], v[172:175], v[196:199], v[18:21]
	v_mfma_f32_16x16x32_bf16 v[6:9], v[164:167], v[204:207], v[6:9]
	v_mfma_f32_16x16x32_bf16 v[2:5], v[172:175], v[204:207], v[2:5]
	v_mfma_f32_16x16x32_bf16 v[54:57], v[168:171], v[184:187], v[54:57]
	v_mfma_f32_16x16x32_bf16 v[50:53], v[176:179], v[184:187], v[50:53]
	v_mfma_f32_16x16x32_bf16 v[38:41], v[168:171], v[192:195], v[38:41]
	v_mfma_f32_16x16x32_bf16 v[34:37], v[176:179], v[192:195], v[34:37]
	v_mfma_f32_16x16x32_bf16 v[22:25], v[168:171], v[200:203], v[22:25]
	v_mfma_f32_16x16x32_bf16 v[18:21], v[176:179], v[200:203], v[18:21]
	v_mfma_f32_16x16x32_bf16 v[6:9], v[168:171], v[208:211], v[6:9]
	v_mfma_f32_16x16x32_bf16 v[2:5], v[176:179], v[208:211], v[2:5]
	s_setprio 0
	s_barrier
	s_add_i32 s24, 0, 0x18000
	v_add_u32_e32 v155, s24, v151
	s_add_i32 s25, 0, 0x1c000
	ds_read_b128 v[140:143], v155
	ds_read_b128 v[144:147], v155 offset:1024
	ds_read_b128 v[156:159], v155 offset:2048
	ds_read_b128 v[160:163], v155 offset:3072
	v_add_u32_e32 v155, s25, v151
	ds_read_b128 v[164:167], v155
	ds_read_b128 v[168:171], v155 offset:1024
	ds_read_b128 v[172:175], v155 offset:2048
	ds_read_b128 v[176:179], v155 offset:3072
	s_add_u32 s6, s56, 0x40000
	s_addc_u32 s7, s57, 0
	s_mov_b32 m0, s63
	v_lshl_add_u64 v[218:219], s[6:7], 0, v[134:135]
	ds_read_b128 v[180:183], v154 offset:32768
	ds_read_b128 v[184:187], v154 offset:33792
	ds_read_b128 v[188:191], v154 offset:34816
	ds_read_b128 v[192:195], v154 offset:35840
	ds_read_b128 v[196:199], v154 offset:36864
	ds_read_b128 v[200:203], v154 offset:37888
	ds_read_b128 v[204:207], v154 offset:38912
	ds_read_b128 v[208:211], v154 offset:39936
	global_load_lds_dwordx4 v[218:219], off
	v_lshl_add_u64 v[218:219], s[6:7], 0, v[132:133]
	s_mov_b32 m0, s64
	s_nop 0
	global_load_lds_dwordx4 v[218:219], off
	s_waitcnt vmcnt(8)
	s_waitcnt lgkmcnt(0)
	s_barrier
	s_setprio 1
	s_waitcnt lgkmcnt(0)
	v_mfma_f32_16x16x32_bf16 v[126:129], v[140:143], v[180:183], v[126:129]
	v_mfma_f32_16x16x32_bf16 v[122:125], v[156:159], v[180:183], v[122:125]
	v_mfma_f32_16x16x32_bf16 v[110:113], v[140:143], v[188:191], v[110:113]
	v_mfma_f32_16x16x32_bf16 v[106:109], v[156:159], v[188:191], v[106:109]
	v_mfma_f32_16x16x32_bf16 v[94:97], v[140:143], v[196:199], v[94:97]
	v_mfma_f32_16x16x32_bf16 v[90:93], v[156:159], v[196:199], v[90:93]
	v_mfma_f32_16x16x32_bf16 v[78:81], v[140:143], v[204:207], v[78:81]
	v_mfma_f32_16x16x32_bf16 v[74:77], v[156:159], v[204:207], v[74:77]
	v_mfma_f32_16x16x32_bf16 v[126:129], v[144:147], v[184:187], v[126:129]
	v_mfma_f32_16x16x32_bf16 v[122:125], v[160:163], v[184:187], v[122:125]
	v_mfma_f32_16x16x32_bf16 v[110:113], v[144:147], v[192:195], v[110:113]
	v_mfma_f32_16x16x32_bf16 v[106:109], v[160:163], v[192:195], v[106:109]
	v_mfma_f32_16x16x32_bf16 v[94:97], v[144:147], v[200:203], v[94:97]
	v_mfma_f32_16x16x32_bf16 v[90:93], v[160:163], v[200:203], v[90:93]
	v_mfma_f32_16x16x32_bf16 v[78:81], v[144:147], v[208:211], v[78:81]
	v_mfma_f32_16x16x32_bf16 v[74:77], v[160:163], v[208:211], v[74:77]
	v_mfma_f32_16x16x32_bf16 v[118:121], v[164:167], v[180:183], v[118:121]
	v_mfma_f32_16x16x32_bf16 v[114:117], v[172:175], v[180:183], v[114:117]
	v_mfma_f32_16x16x32_bf16 v[102:105], v[164:167], v[188:191], v[102:105]
	v_mfma_f32_16x16x32_bf16 v[98:101], v[172:175], v[188:191], v[98:101]
	v_mfma_f32_16x16x32_bf16 v[86:89], v[164:167], v[196:199], v[86:89]
	v_mfma_f32_16x16x32_bf16 v[82:85], v[172:175], v[196:199], v[82:85]
	v_mfma_f32_16x16x32_bf16 v[70:73], v[164:167], v[204:207], v[70:73]
	v_mfma_f32_16x16x32_bf16 v[66:69], v[172:175], v[204:207], v[66:69]
	v_mfma_f32_16x16x32_bf16 v[118:121], v[168:171], v[184:187], v[118:121]
	v_mfma_f32_16x16x32_bf16 v[114:117], v[176:179], v[184:187], v[114:117]
	v_mfma_f32_16x16x32_bf16 v[102:105], v[168:171], v[192:195], v[102:105]
	v_mfma_f32_16x16x32_bf16 v[98:101], v[176:179], v[192:195], v[98:101]
	v_mfma_f32_16x16x32_bf16 v[86:89], v[168:171], v[200:203], v[86:89]
	v_mfma_f32_16x16x32_bf16 v[82:85], v[176:179], v[200:203], v[82:85]
	v_mfma_f32_16x16x32_bf16 v[70:73], v[168:171], v[208:211], v[70:73]
	v_mfma_f32_16x16x32_bf16 v[66:69], v[176:179], v[208:211], v[66:69]
	s_setprio 0
	s_barrier
	s_add_i32 s6, s24, s60
	v_lshl_add_u64 v[148:149], v[148:149], 0, s[84:85]
	s_mov_b32 m0, s6
	ds_read_b128 v[180:183], v154 offset:49152
	ds_read_b128 v[184:187], v154 offset:50176
	ds_read_b128 v[188:191], v154 offset:51200
	ds_read_b128 v[192:195], v154 offset:52224
	ds_read_b128 v[196:199], v154 offset:53248
	ds_read_b128 v[200:203], v154 offset:54272
	ds_read_b128 v[204:207], v154 offset:55296
	ds_read_b128 v[208:211], v154 offset:56320
	global_load_lds_dwordx4 v[148:149], off
	s_add_i32 m0, s6, 0x2000
	s_add_u32 s6, s54, 0x40080
	v_lshl_add_u64 v[148:149], v[212:213], 0, s[84:85]
	s_addc_u32 s7, s55, 0
	s_add_i32 s24, s25, s60
	global_load_lds_dwordx4 v[148:149], off
	v_lshl_add_u64 v[148:149], s[6:7], 0, v[0:1]
	s_mov_b32 m0, s24
	s_nop 0
	global_load_lds_dwordx4 v[148:149], off
	v_lshl_add_u64 v[148:149], s[6:7], 0, v[130:131]
	s_add_i32 m0, s24, 0x2000
	s_nop 0
	global_load_lds_dwordx4 v[148:149], off
	v_lshl_add_u64 v[148:149], v[214:215], 0, s[84:85]
	s_mov_b32 m0, s65
	s_nop 0
	global_load_lds_dwordx4 v[148:149], off
	v_lshl_add_u64 v[148:149], v[216:217], 0, s[84:85]
	s_mov_b32 m0, s66
	s_nop 0
	global_load_lds_dwordx4 v[148:149], off
	s_waitcnt vmcnt(8)
	s_waitcnt lgkmcnt(0)
	s_barrier
	s_setprio 1
	s_waitcnt lgkmcnt(0)
	v_mfma_f32_16x16x32_bf16 v[62:65], v[140:143], v[180:183], v[62:65]
	v_mfma_f32_16x16x32_bf16 v[58:61], v[156:159], v[180:183], v[58:61]
	v_mfma_f32_16x16x32_bf16 v[46:49], v[140:143], v[188:191], v[46:49]
	v_mfma_f32_16x16x32_bf16 v[42:45], v[156:159], v[188:191], v[42:45]
	v_mfma_f32_16x16x32_bf16 v[30:33], v[140:143], v[196:199], v[30:33]
	v_mfma_f32_16x16x32_bf16 v[26:29], v[156:159], v[196:199], v[26:29]
	v_mfma_f32_16x16x32_bf16 v[14:17], v[140:143], v[204:207], v[14:17]
	v_mfma_f32_16x16x32_bf16 v[10:13], v[156:159], v[204:207], v[10:13]
	v_mfma_f32_16x16x32_bf16 v[62:65], v[144:147], v[184:187], v[62:65]
	v_mfma_f32_16x16x32_bf16 v[58:61], v[160:163], v[184:187], v[58:61]
	v_mfma_f32_16x16x32_bf16 v[46:49], v[144:147], v[192:195], v[46:49]
	v_mfma_f32_16x16x32_bf16 v[42:45], v[160:163], v[192:195], v[42:45]
	v_mfma_f32_16x16x32_bf16 v[30:33], v[144:147], v[200:203], v[30:33]
	v_mfma_f32_16x16x32_bf16 v[26:29], v[160:163], v[200:203], v[26:29]
	v_mfma_f32_16x16x32_bf16 v[14:17], v[144:147], v[208:211], v[14:17]
	v_mfma_f32_16x16x32_bf16 v[10:13], v[160:163], v[208:211], v[10:13]
	v_mfma_f32_16x16x32_bf16 v[54:57], v[164:167], v[180:183], v[54:57]
	v_mfma_f32_16x16x32_bf16 v[50:53], v[172:175], v[180:183], v[50:53]
	v_mfma_f32_16x16x32_bf16 v[38:41], v[164:167], v[188:191], v[38:41]
	v_mfma_f32_16x16x32_bf16 v[34:37], v[172:175], v[188:191], v[34:37]
	v_mfma_f32_16x16x32_bf16 v[22:25], v[164:167], v[196:199], v[22:25]
	v_mfma_f32_16x16x32_bf16 v[18:21], v[172:175], v[196:199], v[18:21]
	v_mfma_f32_16x16x32_bf16 v[6:9], v[164:167], v[204:207], v[6:9]
	v_mfma_f32_16x16x32_bf16 v[2:5], v[172:175], v[204:207], v[2:5]
	v_mfma_f32_16x16x32_bf16 v[54:57], v[168:171], v[184:187], v[54:57]
	v_mfma_f32_16x16x32_bf16 v[50:53], v[176:179], v[184:187], v[50:53]
	v_mfma_f32_16x16x32_bf16 v[38:41], v[168:171], v[192:195], v[38:41]
	v_mfma_f32_16x16x32_bf16 v[34:37], v[176:179], v[192:195], v[34:37]
	v_mfma_f32_16x16x32_bf16 v[22:25], v[168:171], v[200:203], v[22:25]
	v_mfma_f32_16x16x32_bf16 v[18:21], v[176:179], v[200:203], v[18:21]
	v_mfma_f32_16x16x32_bf16 v[6:9], v[168:171], v[208:211], v[6:9]
	v_mfma_f32_16x16x32_bf16 v[2:5], v[176:179], v[208:211], v[2:5]
	s_setprio 0
	s_barrier
	s_add_i32 s72, s72, 2
	s_add_u32 s52, s52, 0x100
	s_addc_u32 s53, s53, 0
	s_add_u32 s70, s70, 0x100
	s_addc_u32 s71, s71, 0
	s_cmp_gt_u32 s72, 13
	s_cbranch_scc0 .LBB0_135
	s_and_b64 vcc, exec, s[42:43]
	s_cbranch_vccz .LBB0_138
	s_barrier

.LBB0_231:
	s_add_u32 s6, s0, 0xfffc0080
	s_addc_u32 s7, s1, -1
	s_add_i32 s24, 0, 0x10000
	s_cmp_eq_u32 s71, 12
	s_cselect_b32 s43, s37, s7
	s_cselect_b32 s42, s53, s6
	v_add_u32_e32 v0, s24, v177
	s_cselect_b32 s41, s51, s70
	s_cselect_b32 s40, s58, s59
	s_add_i32 s6, 0, 0x14000
	ds_read_b128 v[10:13], v0
	ds_read_b128 v[14:17], v0 offset:1024
	ds_read_b128 v[26:29], v0 offset:2048
	ds_read_b128 v[30:33], v0 offset:3072
	v_add_u32_e32 v0, s6, v177
	ds_read_b128 v[146:149], v0
	ds_read_b128 v[150:153], v0 offset:1024
	ds_read_b128 v[166:169], v0 offset:2048
	ds_read_b128 v[170:173], v0 offset:3072
	v_lshl_add_u64 v[174:175], s[0:1], 0, v[162:163]
	s_add_i32 m0, s63, 0xc000
	ds_read_b128 v[182:185], v180
	ds_read_b128 v[186:189], v180 offset:1024
	ds_read_b128 v[190:193], v180 offset:2048
	ds_read_b128 v[194:197], v180 offset:3072
	ds_read_b128 v[198:201], v180 offset:4096
	ds_read_b128 v[202:205], v180 offset:5120
	ds_read_b128 v[206:209], v180 offset:6144
	ds_read_b128 v[210:213], v180 offset:7168
	global_load_lds_dwordx4 v[174:175], off
	v_lshl_add_u64 v[174:175], s[0:1], 0, v[164:165]
	s_add_i32 m0, s63, 0xe000
	s_nop 0
	global_load_lds_dwordx4 v[174:175], off
	s_waitcnt vmcnt(8)
	s_waitcnt lgkmcnt(0)
	s_barrier
	s_setprio 1
	s_waitcnt lgkmcnt(0)
	v_mfma_f32_16x16x32_bf16 v[142:145], v[10:13], v[182:185], v[142:145]
	v_mfma_f32_16x16x32_bf16 v[138:141], v[26:29], v[182:185], v[138:141]
	v_mfma_f32_16x16x32_bf16 v[126:129], v[10:13], v[190:193], v[126:129]
	v_mfma_f32_16x16x32_bf16 v[122:125], v[26:29], v[190:193], v[122:125]
	v_mfma_f32_16x16x32_bf16 v[110:113], v[10:13], v[198:201], v[110:113]
	v_mfma_f32_16x16x32_bf16 v[106:109], v[26:29], v[198:201], v[106:109]
	v_mfma_f32_16x16x32_bf16 v[94:97], v[10:13], v[206:209], v[94:97]
	v_mfma_f32_16x16x32_bf16 v[90:93], v[26:29], v[206:209], v[90:93]
	v_mfma_f32_16x16x32_bf16 v[142:145], v[14:17], v[186:189], v[142:145]
	v_mfma_f32_16x16x32_bf16 v[138:141], v[30:33], v[186:189], v[138:141]
	v_mfma_f32_16x16x32_bf16 v[126:129], v[14:17], v[194:197], v[126:129]
	v_mfma_f32_16x16x32_bf16 v[122:125], v[30:33], v[194:197], v[122:125]
	v_mfma_f32_16x16x32_bf16 v[110:113], v[14:17], v[202:205], v[110:113]
	v_mfma_f32_16x16x32_bf16 v[106:109], v[30:33], v[202:205], v[106:109]
	v_mfma_f32_16x16x32_bf16 v[94:97], v[14:17], v[210:213], v[94:97]
	v_mfma_f32_16x16x32_bf16 v[90:93], v[30:33], v[210:213], v[90:93]
	v_mfma_f32_16x16x32_bf16 v[134:137], v[146:149], v[182:185], v[134:137]
	v_mfma_f32_16x16x32_bf16 v[130:133], v[166:169], v[182:185], v[130:133]
	v_mfma_f32_16x16x32_bf16 v[118:121], v[146:149], v[190:193], v[118:121]
	v_mfma_f32_16x16x32_bf16 v[114:117], v[166:169], v[190:193], v[114:117]
	v_mfma_f32_16x16x32_bf16 v[102:105], v[146:149], v[198:201], v[102:105]
	v_mfma_f32_16x16x32_bf16 v[98:101], v[166:169], v[198:201], v[98:101]
	v_mfma_f32_16x16x32_bf16 v[86:89], v[146:149], v[206:209], v[86:89]
	v_mfma_f32_16x16x32_bf16 v[82:85], v[166:169], v[206:209], v[82:85]
	v_mfma_f32_16x16x32_bf16 v[134:137], v[150:153], v[186:189], v[134:137]
	v_mfma_f32_16x16x32_bf16 v[130:133], v[170:173], v[186:189], v[130:133]
	v_mfma_f32_16x16x32_bf16 v[118:121], v[150:153], v[194:197], v[118:121]
	v_mfma_f32_16x16x32_bf16 v[114:117], v[170:173], v[194:197], v[114:117]
	v_mfma_f32_16x16x32_bf16 v[102:105], v[150:153], v[202:205], v[102:105]
	v_mfma_f32_16x16x32_bf16 v[98:101], v[170:173], v[202:205], v[98:101]
	v_mfma_f32_16x16x32_bf16 v[86:89], v[150:153], v[210:213], v[86:89]
	v_mfma_f32_16x16x32_bf16 v[82:85], v[170:173], v[210:213], v[82:85]
	s_setprio 0
	s_barrier
	s_add_i32 s7, s24, s62
	v_lshl_add_u64 v[174:175], s[40:41], 0, v[158:159]
	s_mov_b32 m0, s7
	ds_read_b128 v[182:185], v180 offset:16384
	ds_read_b128 v[186:189], v180 offset:17408
	ds_read_b128 v[190:193], v180 offset:18432
	ds_read_b128 v[194:197], v180 offset:19456
	ds_read_b128 v[198:201], v180 offset:20480
	ds_read_b128 v[202:205], v180 offset:21504
	ds_read_b128 v[206:209], v180 offset:22528
	ds_read_b128 v[210:213], v180 offset:23552
	global_load_lds_dwordx4 v[174:175], off
	s_add_i32 m0, s7, 0x2000
	s_add_u32 s24, s40, 0x40000
	v_lshl_add_u64 v[214:215], s[40:41], 0, v[154:155]
	s_addc_u32 s25, s41, 0
	s_add_i32 s6, s6, s62
	global_load_lds_dwordx4 v[214:215], off
	v_lshl_add_u64 v[216:217], s[24:25], 0, v[158:159]
	s_mov_b32 m0, s6
	v_lshl_add_u64 v[218:219], s[42:43], 0, v[156:157]
	global_load_lds_dwordx4 v[216:217], off
	v_lshl_add_u64 v[216:217], s[24:25], 0, v[154:155]
	s_add_i32 m0, s6, 0x2000
	s_nop 0
	global_load_lds_dwordx4 v[216:217], off
	v_lshl_add_u64 v[216:217], s[42:43], 0, v[160:161]
	s_mov_b32 m0, s63
	s_nop 0
	global_load_lds_dwordx4 v[216:217], off
	s_mov_b32 m0, s64
	s_nop 0
	global_load_lds_dwordx4 v[218:219], off
	s_waitcnt vmcnt(8)
	s_waitcnt lgkmcnt(0)
	s_barrier
	s_setprio 1
	s_waitcnt lgkmcnt(0)
	v_mfma_f32_16x16x32_bf16 v[78:81], v[10:13], v[182:185], v[78:81]
	v_mfma_f32_16x16x32_bf16 v[74:77], v[26:29], v[182:185], v[74:77]
	v_mfma_f32_16x16x32_bf16 v[62:65], v[10:13], v[190:193], v[62:65]
	v_mfma_f32_16x16x32_bf16 v[58:61], v[26:29], v[190:193], v[58:61]
	v_mfma_f32_16x16x32_bf16 v[46:49], v[10:13], v[198:201], v[46:49]
	v_mfma_f32_16x16x32_bf16 v[42:45], v[26:29], v[198:201], v[42:45]
	v_mfma_f32_16x16x32_bf16 v[10:13], v[10:13], v[206:209], v[22:25]
	v_mfma_f32_16x16x32_bf16 v[78:81], v[14:17], v[186:189], v[78:81]
	v_mfma_f32_16x16x32_bf16 v[74:77], v[30:33], v[186:189], v[74:77]
	v_mfma_f32_16x16x32_bf16 v[62:65], v[14:17], v[194:197], v[62:65]
	v_mfma_f32_16x16x32_bf16 v[58:61], v[30:33], v[194:197], v[58:61]
	v_mfma_f32_16x16x32_bf16 v[46:49], v[14:17], v[202:205], v[46:49]
	v_mfma_f32_16x16x32_bf16 v[42:45], v[30:33], v[202:205], v[42:45]
	v_mfma_f32_16x16x32_bf16 v[10:13], v[14:17], v[210:213], v[10:13]
	v_mfma_f32_16x16x32_bf16 v[14:17], v[26:29], v[206:209], v[18:21]
	v_mfma_f32_16x16x32_bf16 v[14:17], v[30:33], v[210:213], v[14:17]
	v_mfma_f32_16x16x32_bf16 v[18:21], v[146:149], v[182:185], v[70:73]
	v_mfma_f32_16x16x32_bf16 v[26:29], v[150:153], v[186:189], v[18:21]
	v_mfma_f32_16x16x32_bf16 v[18:21], v[166:169], v[182:185], v[66:69]
	v_mfma_f32_16x16x32_bf16 v[30:33], v[170:173], v[186:189], v[18:21]
	v_mfma_f32_16x16x32_bf16 v[18:21], v[146:149], v[190:193], v[54:57]
	v_mfma_f32_16x16x32_bf16 v[54:57], v[150:153], v[194:197], v[18:21]
	v_mfma_f32_16x16x32_bf16 v[18:21], v[166:169], v[190:193], v[50:53]
	v_mfma_f32_16x16x32_bf16 v[50:53], v[170:173], v[194:197], v[18:21]
	v_mfma_f32_16x16x32_bf16 v[18:21], v[146:149], v[198:201], v[38:41]
	v_mfma_f32_16x16x32_bf16 v[38:41], v[150:153], v[202:205], v[18:21]
	v_mfma_f32_16x16x32_bf16 v[18:21], v[166:169], v[198:201], v[34:37]
	v_mfma_f32_16x16x32_bf16 v[6:9], v[146:149], v[206:209], v[6:9]
	v_mfma_f32_16x16x32_bf16 v[2:5], v[166:169], v[206:209], v[2:5]
	v_mfma_f32_16x16x32_bf16 v[34:37], v[170:173], v[202:205], v[18:21]
	v_mfma_f32_16x16x32_bf16 v[6:9], v[150:153], v[210:213], v[6:9]
	v_mfma_f32_16x16x32_bf16 v[2:5], v[170:173], v[210:213], v[2:5]
	s_setprio 0
	s_barrier
	s_add_i32 s6, 0, 0x18000
	v_add_u32_e32 v0, s6, v177
	s_add_i32 s7, 0, 0x1c000
	ds_read_b128 v[18:21], v0
	ds_read_b128 v[22:25], v0 offset:1024
	ds_read_b128 v[66:69], v0 offset:2048
	ds_read_b128 v[70:73], v0 offset:3072
	v_add_u32_e32 v0, s7, v177
	ds_read_b128 v[146:149], v0
	ds_read_b128 v[150:153], v0 offset:1024
	ds_read_b128 v[166:169], v0 offset:2048
	ds_read_b128 v[170:173], v0 offset:3072
	s_add_u32 s24, s42, 0x40000
	s_addc_u32 s25, s43, 0
	s_mov_b32 m0, s65
	v_lshl_add_u64 v[220:221], s[24:25], 0, v[160:161]
	ds_read_b128 v[182:185], v180 offset:32768
	ds_read_b128 v[186:189], v180 offset:33792
	ds_read_b128 v[190:193], v180 offset:34816
	ds_read_b128 v[194:197], v180 offset:35840
	ds_read_b128 v[198:201], v180 offset:36864
	ds_read_b128 v[202:205], v180 offset:37888
	ds_read_b128 v[206:209], v180 offset:38912
	ds_read_b128 v[210:213], v180 offset:39936
	global_load_lds_dwordx4 v[220:221], off
	v_lshl_add_u64 v[220:221], s[24:25], 0, v[156:157]
	s_mov_b32 m0, s66
	s_nop 0
	global_load_lds_dwordx4 v[220:221], off
	s_waitcnt vmcnt(8)
	s_waitcnt lgkmcnt(0)
	s_barrier
	s_setprio 1
	s_waitcnt lgkmcnt(0)
	v_mfma_f32_16x16x32_bf16 v[142:145], v[18:21], v[182:185], v[142:145]
	v_mfma_f32_16x16x32_bf16 v[138:141], v[66:69], v[182:185], v[138:141]
	v_mfma_f32_16x16x32_bf16 v[126:129], v[18:21], v[190:193], v[126:129]
	v_mfma_f32_16x16x32_bf16 v[122:125], v[66:69], v[190:193], v[122:125]
	v_mfma_f32_16x16x32_bf16 v[110:113], v[18:21], v[198:201], v[110:113]
	v_mfma_f32_16x16x32_bf16 v[106:109], v[66:69], v[198:201], v[106:109]
	v_mfma_f32_16x16x32_bf16 v[94:97], v[18:21], v[206:209], v[94:97]
	v_mfma_f32_16x16x32_bf16 v[90:93], v[66:69], v[206:209], v[90:93]
	v_mfma_f32_16x16x32_bf16 v[142:145], v[22:25], v[186:189], v[142:145]
	v_mfma_f32_16x16x32_bf16 v[138:141], v[70:73], v[186:189], v[138:141]
	v_mfma_f32_16x16x32_bf16 v[126:129], v[22:25], v[194:197], v[126:129]
	v_mfma_f32_16x16x32_bf16 v[122:125], v[70:73], v[194:197], v[122:125]
	v_mfma_f32_16x16x32_bf16 v[110:113], v[22:25], v[202:205], v[110:113]
	v_mfma_f32_16x16x32_bf16 v[106:109], v[70:73], v[202:205], v[106:109]
	v_mfma_f32_16x16x32_bf16 v[94:97], v[22:25], v[210:213], v[94:97]
	v_mfma_f32_16x16x32_bf16 v[90:93], v[70:73], v[210:213], v[90:93]
	v_mfma_f32_16x16x32_bf16 v[134:137], v[146:149], v[182:185], v[134:137]
	v_mfma_f32_16x16x32_bf16 v[130:133], v[166:169], v[182:185], v[130:133]
	v_mfma_f32_16x16x32_bf16 v[118:121], v[146:149], v[190:193], v[118:121]
	v_mfma_f32_16x16x32_bf16 v[114:117], v[166:169], v[190:193], v[114:117]
	v_mfma_f32_16x16x32_bf16 v[102:105], v[146:149], v[198:201], v[102:105]
	v_mfma_f32_16x16x32_bf16 v[98:101], v[166:169], v[198:201], v[98:101]
	v_mfma_f32_16x16x32_bf16 v[86:89], v[146:149], v[206:209], v[86:89]
	v_mfma_f32_16x16x32_bf16 v[82:85], v[166:169], v[206:209], v[82:85]
	v_mfma_f32_16x16x32_bf16 v[134:137], v[150:153], v[186:189], v[134:137]
	v_mfma_f32_16x16x32_bf16 v[130:133], v[170:173], v[186:189], v[130:133]
	v_mfma_f32_16x16x32_bf16 v[118:121], v[150:153], v[194:197], v[118:121]
	v_mfma_f32_16x16x32_bf16 v[114:117], v[170:173], v[194:197], v[114:117]
	v_mfma_f32_16x16x32_bf16 v[102:105], v[150:153], v[202:205], v[102:105]
	v_mfma_f32_16x16x32_bf16 v[98:101], v[170:173], v[202:205], v[98:101]
	v_mfma_f32_16x16x32_bf16 v[86:89], v[150:153], v[210:213], v[86:89]
	v_mfma_f32_16x16x32_bf16 v[82:85], v[170:173], v[210:213], v[82:85]
	s_setprio 0
	s_barrier
	s_add_i32 s6, s6, s62
	v_lshl_add_u64 v[174:175], v[174:175], 0, s[84:85]
	s_mov_b32 m0, s6
	ds_read_b128 v[182:185], v180 offset:49152
	ds_read_b128 v[186:189], v180 offset:50176
	ds_read_b128 v[190:193], v180 offset:51200
	ds_read_b128 v[194:197], v180 offset:52224
	ds_read_b128 v[198:201], v180 offset:53248
	ds_read_b128 v[202:205], v180 offset:54272
	ds_read_b128 v[206:209], v180 offset:55296
	ds_read_b128 v[210:213], v180 offset:56320
	global_load_lds_dwordx4 v[174:175], off
	s_add_i32 m0, s6, 0x2000
	s_add_u32 s24, s40, 0x40080
	v_lshl_add_u64 v[174:175], v[214:215], 0, s[84:85]
	s_addc_u32 s25, s41, 0
	s_add_i32 s6, s7, s62
	global_load_lds_dwordx4 v[174:175], off
	v_lshl_add_u64 v[174:175], s[24:25], 0, v[158:159]
	s_mov_b32 m0, s6
	s_nop 0
	global_load_lds_dwordx4 v[174:175], off
	v_lshl_add_u64 v[174:175], s[24:25], 0, v[154:155]
	s_add_i32 m0, s6, 0x2000
	s_nop 0
	global_load_lds_dwordx4 v[174:175], off
	v_lshl_add_u64 v[174:175], v[216:217], 0, s[84:85]
	s_mov_b32 m0, s8
	s_nop 0
	global_load_lds_dwordx4 v[174:175], off
	v_lshl_add_u64 v[174:175], v[218:219], 0, s[84:85]
	s_mov_b32 m0, s67
	s_nop 0
	global_load_lds_dwordx4 v[174:175], off
	s_waitcnt vmcnt(8)
	s_waitcnt lgkmcnt(0)
	s_barrier
	s_setprio 1
	s_waitcnt lgkmcnt(0)
	v_mfma_f32_16x16x32_bf16 v[78:81], v[18:21], v[182:185], v[78:81]
	v_mfma_f32_16x16x32_bf16 v[62:65], v[18:21], v[190:193], v[62:65]
	v_mfma_f32_16x16x32_bf16 v[46:49], v[18:21], v[198:201], v[46:49]
	v_mfma_f32_16x16x32_bf16 v[10:13], v[18:21], v[206:209], v[10:13]
	v_mfma_f32_16x16x32_bf16 v[78:81], v[22:25], v[186:189], v[78:81]
	v_mfma_f32_16x16x32_bf16 v[74:77], v[66:69], v[182:185], v[74:77]
	v_mfma_f32_16x16x32_bf16 v[62:65], v[22:25], v[194:197], v[62:65]
	v_mfma_f32_16x16x32_bf16 v[58:61], v[66:69], v[190:193], v[58:61]
	v_mfma_f32_16x16x32_bf16 v[46:49], v[22:25], v[202:205], v[46:49]
	v_mfma_f32_16x16x32_bf16 v[42:45], v[66:69], v[198:201], v[42:45]
	v_mfma_f32_16x16x32_bf16 v[22:25], v[22:25], v[210:213], v[10:13]
	v_mfma_f32_16x16x32_bf16 v[10:13], v[66:69], v[206:209], v[14:17]
	v_mfma_f32_16x16x32_bf16 v[74:77], v[70:73], v[186:189], v[74:77]
	v_mfma_f32_16x16x32_bf16 v[58:61], v[70:73], v[194:197], v[58:61]
	v_mfma_f32_16x16x32_bf16 v[42:45], v[70:73], v[202:205], v[42:45]
	v_mfma_f32_16x16x32_bf16 v[18:21], v[70:73], v[210:213], v[10:13]
	v_mfma_f32_16x16x32_bf16 v[10:13], v[146:149], v[182:185], v[26:29]
	v_mfma_f32_16x16x32_bf16 v[70:73], v[150:153], v[186:189], v[10:13]
	v_mfma_f32_16x16x32_bf16 v[10:13], v[166:169], v[182:185], v[30:33]
	v_mfma_f32_16x16x32_bf16 v[66:69], v[170:173], v[186:189], v[10:13]
	v_mfma_f32_16x16x32_bf16 v[10:13], v[146:149], v[190:193], v[54:57]
	v_mfma_f32_16x16x32_bf16 v[54:57], v[150:153], v[194:197], v[10:13]
	v_mfma_f32_16x16x32_bf16 v[10:13], v[166:169], v[190:193], v[50:53]
	v_mfma_f32_16x16x32_bf16 v[50:53], v[170:173], v[194:197], v[10:13]
	v_mfma_f32_16x16x32_bf16 v[10:13], v[146:149], v[198:201], v[38:41]
	v_mfma_f32_16x16x32_bf16 v[38:41], v[150:153], v[202:205], v[10:13]
	v_mfma_f32_16x16x32_bf16 v[10:13], v[166:169], v[198:201], v[34:37]
	v_mfma_f32_16x16x32_bf16 v[6:9], v[146:149], v[206:209], v[6:9]
	v_mfma_f32_16x16x32_bf16 v[2:5], v[166:169], v[206:209], v[2:5]
	v_mfma_f32_16x16x32_bf16 v[34:37], v[170:173], v[202:205], v[10:13]
	v_mfma_f32_16x16x32_bf16 v[6:9], v[150:153], v[210:213], v[6:9]
	v_mfma_f32_16x16x32_bf16 v[2:5], v[170:173], v[210:213], v[2:5]
	s_setprio 0
	s_barrier
	s_add_i32 s71, s71, 2
	s_add_u32 s0, s0, 0x100
	s_addc_u32 s1, s1, 0
	s_add_u32 s59, s59, 0x100
	s_addc_u32 s70, s70, 0
	s_cmp_gt_u32 s71, 13
	s_cbranch_scc0 .LBB0_231
	s_and_b64 vcc, exec, s[48:49]
	s_cbranch_vccz .LBB0_234
	s_barrier

.LBB0_560:
	s_add_u32 s6, s40, 0xfffc0080
	s_addc_u32 s7, s41, -1
	s_add_i32 s24, 0, 0x10000
	s_cmp_eq_u32 s66, 12
	s_cselect_b32 s53, s47, s7
	s_cselect_b32 s52, s62, s6
	v_add_u32_e32 v0, s24, v193
	s_cselect_b32 s43, s45, s65
	s_cselect_b32 s42, s63, s64
	s_add_i32 s6, 0, 0x14000
	ds_read_b128 v[74:77], v0
	ds_read_b128 v[86:89], v0 offset:1024
	ds_read_b128 v[98:101], v0 offset:2048
	ds_read_b128 v[102:105], v0 offset:3072
	v_add_u32_e32 v0, s6, v193
	ds_read_b128 v[118:121], v0
	ds_read_b128 v[126:129], v0 offset:1024
	ds_read_b128 v[138:141], v0 offset:2048
	ds_read_b128 v[142:145], v0 offset:3072
	v_lshl_add_u64 v[188:189], s[40:41], 0, v[180:181]
	s_add_i32 m0, s55, 0xc000
	ds_read_b128 v[154:157], v213
	ds_read_b128 v[162:165], v213 offset:1024
	ds_read_b128 v[184:187], v213 offset:2048
	ds_read_b128 v[194:197], v213 offset:3072
	ds_read_b128 v[198:201], v213 offset:4096
	ds_read_b128 v[214:217], v213 offset:5120
	ds_read_b128 v[218:221], v213 offset:6144
	ds_read_b128 v[222:225], v213 offset:7168
	global_load_lds_dwordx4 v[188:189], off
	v_lshl_add_u64 v[188:189], s[40:41], 0, v[182:183]
	s_add_i32 m0, s55, 0xe000
	s_nop 0
	global_load_lds_dwordx4 v[188:189], off
	s_waitcnt vmcnt(8)
	s_waitcnt lgkmcnt(0)
	s_barrier
	s_setprio 1
	s_waitcnt lgkmcnt(0)
	v_mfma_f32_16x16x32_bf16 v[166:169], v[74:77], v[154:157], v[166:169]
	v_mfma_f32_16x16x32_bf16 v[158:161], v[98:101], v[154:157], v[158:161]
	v_mfma_f32_16x16x32_bf16 v[134:137], v[74:77], v[184:187], v[134:137]
	v_mfma_f32_16x16x32_bf16 v[130:133], v[98:101], v[184:187], v[130:133]
	v_mfma_f32_16x16x32_bf16 v[110:113], v[74:77], v[198:201], v[110:113]
	v_mfma_f32_16x16x32_bf16 v[106:109], v[98:101], v[198:201], v[106:109]
	v_mfma_f32_16x16x32_bf16 v[82:85], v[74:77], v[218:221], v[82:85]
	v_mfma_f32_16x16x32_bf16 v[78:81], v[98:101], v[218:221], v[78:81]
	v_mfma_f32_16x16x32_bf16 v[166:169], v[86:89], v[162:165], v[166:169]
	v_mfma_f32_16x16x32_bf16 v[158:161], v[102:105], v[162:165], v[158:161]
	v_mfma_f32_16x16x32_bf16 v[134:137], v[86:89], v[194:197], v[134:137]
	v_mfma_f32_16x16x32_bf16 v[130:133], v[102:105], v[194:197], v[130:133]
	v_mfma_f32_16x16x32_bf16 v[110:113], v[86:89], v[214:217], v[110:113]
	v_mfma_f32_16x16x32_bf16 v[106:109], v[102:105], v[214:217], v[106:109]
	v_mfma_f32_16x16x32_bf16 v[82:85], v[86:89], v[222:225], v[82:85]
	v_mfma_f32_16x16x32_bf16 v[78:81], v[102:105], v[222:225], v[78:81]
	v_mfma_f32_16x16x32_bf16 v[150:153], v[118:121], v[154:157], v[150:153]
	v_mfma_f32_16x16x32_bf16 v[146:149], v[138:141], v[154:157], v[146:149]
	v_mfma_f32_16x16x32_bf16 v[122:125], v[118:121], v[184:187], v[122:125]
	v_mfma_f32_16x16x32_bf16 v[114:117], v[138:141], v[184:187], v[114:117]
	v_mfma_f32_16x16x32_bf16 v[94:97], v[118:121], v[198:201], v[94:97]
	v_mfma_f32_16x16x32_bf16 v[90:93], v[138:141], v[198:201], v[90:93]
	v_mfma_f32_16x16x32_bf16 v[70:73], v[118:121], v[218:221], v[70:73]
	v_mfma_f32_16x16x32_bf16 v[66:69], v[138:141], v[218:221], v[66:69]
	v_mfma_f32_16x16x32_bf16 v[150:153], v[126:129], v[162:165], v[150:153]
	v_mfma_f32_16x16x32_bf16 v[146:149], v[142:145], v[162:165], v[146:149]
	v_mfma_f32_16x16x32_bf16 v[122:125], v[126:129], v[194:197], v[122:125]
	v_mfma_f32_16x16x32_bf16 v[114:117], v[142:145], v[194:197], v[114:117]
	v_mfma_f32_16x16x32_bf16 v[94:97], v[126:129], v[214:217], v[94:97]
	v_mfma_f32_16x16x32_bf16 v[90:93], v[142:145], v[214:217], v[90:93]
	v_mfma_f32_16x16x32_bf16 v[70:73], v[126:129], v[222:225], v[70:73]
	v_mfma_f32_16x16x32_bf16 v[66:69], v[142:145], v[222:225], v[66:69]
	s_setprio 0
	s_barrier
	s_add_i32 s7, s24, s54
	v_lshl_add_u64 v[188:189], s[42:43], 0, v[174:175]
	s_mov_b32 m0, s7
	ds_read_b128 v[154:157], v213 offset:16384
	ds_read_b128 v[162:165], v213 offset:17408
	ds_read_b128 v[184:187], v213 offset:18432
	ds_read_b128 v[194:197], v213 offset:19456
	ds_read_b128 v[198:201], v213 offset:20480
	ds_read_b128 v[214:217], v213 offset:21504
	ds_read_b128 v[218:221], v213 offset:22528
	ds_read_b128 v[222:225], v213 offset:23552
	global_load_lds_dwordx4 v[188:189], off
	s_add_i32 m0, s7, 0x2000
	s_add_u32 s24, s42, 0x40000
	v_lshl_add_u64 v[202:203], s[42:43], 0, v[170:171]
	s_addc_u32 s25, s43, 0
	s_add_i32 s6, s6, s54
	global_load_lds_dwordx4 v[202:203], off
	v_lshl_add_u64 v[226:227], s[24:25], 0, v[174:175]
	s_mov_b32 m0, s6
	v_lshl_add_u64 v[230:231], s[52:53], 0, v[172:173]
	global_load_lds_dwordx4 v[226:227], off
	v_lshl_add_u64 v[226:227], s[24:25], 0, v[170:171]
	s_add_i32 m0, s6, 0x2000
	s_nop 0
	global_load_lds_dwordx4 v[226:227], off
	v_lshl_add_u64 v[226:227], s[52:53], 0, v[176:177]
	s_mov_b32 m0, s55
	s_nop 0
	global_load_lds_dwordx4 v[226:227], off
	s_mov_b32 m0, s56
	s_nop 0
	global_load_lds_dwordx4 v[230:231], off
	s_waitcnt vmcnt(8)
	s_waitcnt lgkmcnt(0)
	s_barrier
	s_setprio 1
	s_waitcnt lgkmcnt(0)
	v_mfma_f32_16x16x32_bf16 v[62:65], v[74:77], v[154:157], v[62:65]
	v_mfma_f32_16x16x32_bf16 v[58:61], v[98:101], v[154:157], v[58:61]
	v_mfma_f32_16x16x32_bf16 v[46:49], v[74:77], v[184:187], v[46:49]
	v_mfma_f32_16x16x32_bf16 v[42:45], v[98:101], v[184:187], v[42:45]
	v_mfma_f32_16x16x32_bf16 v[30:33], v[74:77], v[198:201], v[30:33]
	v_mfma_f32_16x16x32_bf16 v[26:29], v[98:101], v[198:201], v[26:29]
	v_mfma_f32_16x16x32_bf16 v[14:17], v[74:77], v[218:221], v[14:17]
	v_mfma_f32_16x16x32_bf16 v[10:13], v[98:101], v[218:221], v[10:13]
	v_mfma_f32_16x16x32_bf16 v[62:65], v[86:89], v[162:165], v[62:65]
	v_mfma_f32_16x16x32_bf16 v[58:61], v[102:105], v[162:165], v[58:61]
	v_mfma_f32_16x16x32_bf16 v[46:49], v[86:89], v[194:197], v[46:49]
	v_mfma_f32_16x16x32_bf16 v[42:45], v[102:105], v[194:197], v[42:45]
	v_mfma_f32_16x16x32_bf16 v[30:33], v[86:89], v[214:217], v[30:33]
	v_mfma_f32_16x16x32_bf16 v[26:29], v[102:105], v[214:217], v[26:29]
	v_mfma_f32_16x16x32_bf16 v[14:17], v[86:89], v[222:225], v[14:17]
	v_mfma_f32_16x16x32_bf16 v[10:13], v[102:105], v[222:225], v[10:13]
	v_mfma_f32_16x16x32_bf16 v[54:57], v[118:121], v[154:157], v[54:57]
	v_mfma_f32_16x16x32_bf16 v[50:53], v[138:141], v[154:157], v[50:53]
	v_mfma_f32_16x16x32_bf16 v[38:41], v[118:121], v[184:187], v[38:41]
	v_mfma_f32_16x16x32_bf16 v[34:37], v[138:141], v[184:187], v[34:37]
	v_mfma_f32_16x16x32_bf16 v[22:25], v[118:121], v[198:201], v[22:25]
	v_mfma_f32_16x16x32_bf16 v[18:21], v[138:141], v[198:201], v[18:21]
	v_mfma_f32_16x16x32_bf16 v[6:9], v[118:121], v[218:221], v[6:9]
	v_mfma_f32_16x16x32_bf16 v[2:5], v[138:141], v[218:221], v[2:5]
	v_mfma_f32_16x16x32_bf16 v[54:57], v[126:129], v[162:165], v[54:57]
	v_mfma_f32_16x16x32_bf16 v[50:53], v[142:145], v[162:165], v[50:53]
	v_mfma_f32_16x16x32_bf16 v[38:41], v[126:129], v[194:197], v[38:41]
	v_mfma_f32_16x16x32_bf16 v[34:37], v[142:145], v[194:197], v[34:37]
	v_mfma_f32_16x16x32_bf16 v[22:25], v[126:129], v[214:217], v[22:25]
	v_mfma_f32_16x16x32_bf16 v[18:21], v[142:145], v[214:217], v[18:21]
	v_mfma_f32_16x16x32_bf16 v[6:9], v[126:129], v[222:225], v[6:9]
	v_mfma_f32_16x16x32_bf16 v[2:5], v[142:145], v[222:225], v[2:5]
	s_setprio 0
	s_barrier
	s_add_i32 s6, 0, 0x18000
	v_add_u32_e32 v0, s6, v193
	s_add_i32 s7, 0, 0x1c000
	ds_read_b128 v[74:77], v0
	ds_read_b128 v[86:89], v0 offset:1024
	ds_read_b128 v[98:101], v0 offset:2048
	ds_read_b128 v[102:105], v0 offset:3072
	v_add_u32_e32 v0, s7, v193
	ds_read_b128 v[118:121], v0
	ds_read_b128 v[126:129], v0 offset:1024
	ds_read_b128 v[138:141], v0 offset:2048
	ds_read_b128 v[142:145], v0 offset:3072
	s_add_u32 s24, s52, 0x40000
	s_addc_u32 s25, s53, 0
	s_mov_b32 m0, s57
	v_lshl_add_u64 v[232:233], s[24:25], 0, v[176:177]
	ds_read_b128 v[154:157], v213 offset:32768
	ds_read_b128 v[162:165], v213 offset:33792
	ds_read_b128 v[184:187], v213 offset:34816
	ds_read_b128 v[194:197], v213 offset:35840
	ds_read_b128 v[198:201], v213 offset:36864
	ds_read_b128 v[214:217], v213 offset:37888
	ds_read_b128 v[218:221], v213 offset:38912
	ds_read_b128 v[222:225], v213 offset:39936
	global_load_lds_dwordx4 v[232:233], off
	v_lshl_add_u64 v[232:233], s[24:25], 0, v[172:173]
	s_mov_b32 m0, s58
	s_nop 0
	global_load_lds_dwordx4 v[232:233], off
	s_waitcnt vmcnt(8)
	s_waitcnt lgkmcnt(0)
	s_barrier
	s_setprio 1
	s_waitcnt lgkmcnt(0)
	v_mfma_f32_16x16x32_bf16 v[166:169], v[74:77], v[154:157], v[166:169]
	v_mfma_f32_16x16x32_bf16 v[158:161], v[98:101], v[154:157], v[158:161]
	v_mfma_f32_16x16x32_bf16 v[134:137], v[74:77], v[184:187], v[134:137]
	v_mfma_f32_16x16x32_bf16 v[130:133], v[98:101], v[184:187], v[130:133]
	v_mfma_f32_16x16x32_bf16 v[110:113], v[74:77], v[198:201], v[110:113]
	v_mfma_f32_16x16x32_bf16 v[106:109], v[98:101], v[198:201], v[106:109]
	v_mfma_f32_16x16x32_bf16 v[82:85], v[74:77], v[218:221], v[82:85]
	v_mfma_f32_16x16x32_bf16 v[78:81], v[98:101], v[218:221], v[78:81]
	v_mfma_f32_16x16x32_bf16 v[166:169], v[86:89], v[162:165], v[166:169]
	v_mfma_f32_16x16x32_bf16 v[158:161], v[102:105], v[162:165], v[158:161]
	v_mfma_f32_16x16x32_bf16 v[134:137], v[86:89], v[194:197], v[134:137]
	v_mfma_f32_16x16x32_bf16 v[130:133], v[102:105], v[194:197], v[130:133]
	v_mfma_f32_16x16x32_bf16 v[110:113], v[86:89], v[214:217], v[110:113]
	v_mfma_f32_16x16x32_bf16 v[106:109], v[102:105], v[214:217], v[106:109]
	v_mfma_f32_16x16x32_bf16 v[82:85], v[86:89], v[222:225], v[82:85]
	v_mfma_f32_16x16x32_bf16 v[78:81], v[102:105], v[222:225], v[78:81]
	v_mfma_f32_16x16x32_bf16 v[150:153], v[118:121], v[154:157], v[150:153]
	v_mfma_f32_16x16x32_bf16 v[146:149], v[138:141], v[154:157], v[146:149]
	v_mfma_f32_16x16x32_bf16 v[122:125], v[118:121], v[184:187], v[122:125]
	v_mfma_f32_16x16x32_bf16 v[114:117], v[138:141], v[184:187], v[114:117]
	v_mfma_f32_16x16x32_bf16 v[94:97], v[118:121], v[198:201], v[94:97]
	v_mfma_f32_16x16x32_bf16 v[90:93], v[138:141], v[198:201], v[90:93]
	v_mfma_f32_16x16x32_bf16 v[70:73], v[118:121], v[218:221], v[70:73]
	v_mfma_f32_16x16x32_bf16 v[66:69], v[138:141], v[218:221], v[66:69]
	v_mfma_f32_16x16x32_bf16 v[150:153], v[126:129], v[162:165], v[150:153]
	v_mfma_f32_16x16x32_bf16 v[146:149], v[142:145], v[162:165], v[146:149]
	v_mfma_f32_16x16x32_bf16 v[122:125], v[126:129], v[194:197], v[122:125]
	v_mfma_f32_16x16x32_bf16 v[114:117], v[142:145], v[194:197], v[114:117]
	v_mfma_f32_16x16x32_bf16 v[94:97], v[126:129], v[214:217], v[94:97]
	v_mfma_f32_16x16x32_bf16 v[90:93], v[142:145], v[214:217], v[90:93]
	v_mfma_f32_16x16x32_bf16 v[70:73], v[126:129], v[222:225], v[70:73]
	v_mfma_f32_16x16x32_bf16 v[66:69], v[142:145], v[222:225], v[66:69]
	s_setprio 0
	s_barrier
	s_add_i32 s6, s6, s54
	v_lshl_add_u64 v[188:189], v[188:189], 0, s[84:85]
	s_mov_b32 m0, s6
	ds_read_b128 v[154:157], v213 offset:49152
	ds_read_b128 v[162:165], v213 offset:50176
	ds_read_b128 v[184:187], v213 offset:51200
	ds_read_b128 v[194:197], v213 offset:52224
	ds_read_b128 v[198:201], v213 offset:53248
	ds_read_b128 v[214:217], v213 offset:54272
	ds_read_b128 v[218:221], v213 offset:55296
	ds_read_b128 v[222:225], v213 offset:56320
	global_load_lds_dwordx4 v[188:189], off
	s_add_i32 m0, s6, 0x2000
	s_add_u32 s24, s42, 0x40080
	v_lshl_add_u64 v[188:189], v[202:203], 0, s[84:85]
	s_addc_u32 s25, s43, 0
	s_add_i32 s6, s7, s54
	global_load_lds_dwordx4 v[188:189], off
	v_lshl_add_u64 v[188:189], s[24:25], 0, v[174:175]
	s_mov_b32 m0, s6
	s_nop 0
	global_load_lds_dwordx4 v[188:189], off
	v_lshl_add_u64 v[188:189], s[24:25], 0, v[170:171]
	s_add_i32 m0, s6, 0x2000
	s_nop 0
	global_load_lds_dwordx4 v[188:189], off
	v_lshl_add_u64 v[188:189], v[226:227], 0, s[84:85]
	s_mov_b32 m0, s59
	s_nop 0
	global_load_lds_dwordx4 v[188:189], off
	v_lshl_add_u64 v[188:189], v[230:231], 0, s[84:85]
	s_mov_b32 m0, s60
	s_nop 0
	global_load_lds_dwordx4 v[188:189], off
	s_waitcnt vmcnt(8)
	s_waitcnt lgkmcnt(0)
	s_barrier
	s_setprio 1
	s_waitcnt lgkmcnt(0)
	v_mfma_f32_16x16x32_bf16 v[62:65], v[74:77], v[154:157], v[62:65]
	v_mfma_f32_16x16x32_bf16 v[58:61], v[98:101], v[154:157], v[58:61]
	v_mfma_f32_16x16x32_bf16 v[46:49], v[74:77], v[184:187], v[46:49]
	v_mfma_f32_16x16x32_bf16 v[42:45], v[98:101], v[184:187], v[42:45]
	v_mfma_f32_16x16x32_bf16 v[30:33], v[74:77], v[198:201], v[30:33]
	v_mfma_f32_16x16x32_bf16 v[26:29], v[98:101], v[198:201], v[26:29]
	v_mfma_f32_16x16x32_bf16 v[14:17], v[74:77], v[218:221], v[14:17]
	v_mfma_f32_16x16x32_bf16 v[10:13], v[98:101], v[218:221], v[10:13]
	v_mfma_f32_16x16x32_bf16 v[62:65], v[86:89], v[162:165], v[62:65]
	v_mfma_f32_16x16x32_bf16 v[58:61], v[102:105], v[162:165], v[58:61]
	v_mfma_f32_16x16x32_bf16 v[46:49], v[86:89], v[194:197], v[46:49]
	v_mfma_f32_16x16x32_bf16 v[42:45], v[102:105], v[194:197], v[42:45]
	v_mfma_f32_16x16x32_bf16 v[30:33], v[86:89], v[214:217], v[30:33]
	v_mfma_f32_16x16x32_bf16 v[26:29], v[102:105], v[214:217], v[26:29]
	v_mfma_f32_16x16x32_bf16 v[14:17], v[86:89], v[222:225], v[14:17]
	v_mfma_f32_16x16x32_bf16 v[10:13], v[102:105], v[222:225], v[10:13]
	v_mfma_f32_16x16x32_bf16 v[54:57], v[118:121], v[154:157], v[54:57]
	v_mfma_f32_16x16x32_bf16 v[50:53], v[138:141], v[154:157], v[50:53]
	v_mfma_f32_16x16x32_bf16 v[38:41], v[118:121], v[184:187], v[38:41]
	v_mfma_f32_16x16x32_bf16 v[34:37], v[138:141], v[184:187], v[34:37]
	v_mfma_f32_16x16x32_bf16 v[22:25], v[118:121], v[198:201], v[22:25]
	v_mfma_f32_16x16x32_bf16 v[18:21], v[138:141], v[198:201], v[18:21]
	v_mfma_f32_16x16x32_bf16 v[6:9], v[118:121], v[218:221], v[6:9]
	v_mfma_f32_16x16x32_bf16 v[2:5], v[138:141], v[218:221], v[2:5]
	v_mfma_f32_16x16x32_bf16 v[54:57], v[126:129], v[162:165], v[54:57]
	v_mfma_f32_16x16x32_bf16 v[50:53], v[142:145], v[162:165], v[50:53]
	v_mfma_f32_16x16x32_bf16 v[38:41], v[126:129], v[194:197], v[38:41]
	v_mfma_f32_16x16x32_bf16 v[34:37], v[142:145], v[194:197], v[34:37]
	v_mfma_f32_16x16x32_bf16 v[22:25], v[126:129], v[214:217], v[22:25]
	v_mfma_f32_16x16x32_bf16 v[18:21], v[142:145], v[214:217], v[18:21]
	v_mfma_f32_16x16x32_bf16 v[6:9], v[126:129], v[222:225], v[6:9]
	v_mfma_f32_16x16x32_bf16 v[2:5], v[142:145], v[222:225], v[2:5]
	s_setprio 0
	s_barrier
	s_add_i32 s66, s66, 2
	s_add_u32 s40, s40, 0x100
	s_addc_u32 s41, s41, 0
	s_add_u32 s64, s64, 0x100
	s_addc_u32 s65, s65, 0
	s_cmp_gt_u32 s66, 13
	s_cbranch_scc0 .LBB0_560
	s_and_b64 vcc, exec, s[26:27]
	s_cbranch_vccz .LBB0_563
	s_barrier

.LBB0_763:
	s_add_i32 s25, s24, 2
	s_add_u32 s6, s50, 0x80
	s_addc_u32 s7, s51, 0
	s_add_i32 s55, 0, 0x10000
	s_cmp_eq_u32 s67, s24
	s_cselect_b32 s53, s41, s7
	s_cselect_b32 s52, s40, s6
	s_cselect_b32 s7, s49, s54
	s_cselect_b32 s6, s48, s37
	s_add_i32 s24, 0, 0x14000
	v_add_u32_e32 v142, s55, v188
	v_add_u32_e32 v171, s24, v188
	ds_read_b128 v[122:125], v142
	ds_read_b128 v[134:137], v142 offset:1024
	ds_read_b128 v[138:141], v142 offset:2048
	ds_read_b128 v[142:145], v142 offset:3072
	ds_read_b128 v[146:149], v171
	ds_read_b128 v[150:153], v171 offset:1024
	ds_read_b128 v[154:157], v171 offset:2048
	ds_read_b128 v[172:175], v171 offset:3072
	v_lshl_add_u64 v[184:185], s[50:51], 0, v[166:167]
	s_add_i32 m0, s57, 0xc000
	ds_read_b128 v[176:179], v190
	ds_read_b128 v[180:183], v190 offset:1024
	ds_read_b128 v[192:195], v190 offset:2048
	ds_read_b128 v[196:199], v190 offset:3072
	ds_read_b128 v[200:203], v190 offset:4096
	ds_read_b128 v[204:207], v190 offset:5120
	ds_read_b128 v[208:211], v190 offset:6144
	ds_read_b128 v[212:215], v190 offset:7168
	global_load_lds_dwordx4 v[184:185], off
	v_lshl_add_u64 v[184:185], s[50:51], 0, v[168:169]
	s_add_i32 m0, s57, 0xe000
	s_nop 0
	global_load_lds_dwordx4 v[184:185], off
	s_waitcnt vmcnt(8)
	s_waitcnt lgkmcnt(0)
	s_barrier
	s_setprio 1
	s_waitcnt lgkmcnt(0)
	v_mfma_f32_16x16x32_bf16 v[130:133], v[122:125], v[176:179], v[130:133]
	v_mfma_f32_16x16x32_bf16 v[126:129], v[138:141], v[176:179], v[126:129]
	v_mfma_f32_16x16x32_bf16 v[110:113], v[122:125], v[192:195], v[110:113]
	v_mfma_f32_16x16x32_bf16 v[106:109], v[138:141], v[192:195], v[106:109]
	v_mfma_f32_16x16x32_bf16 v[94:97], v[122:125], v[200:203], v[94:97]
	v_mfma_f32_16x16x32_bf16 v[90:93], v[138:141], v[200:203], v[90:93]
	v_mfma_f32_16x16x32_bf16 v[78:81], v[122:125], v[208:211], v[78:81]
	v_mfma_f32_16x16x32_bf16 v[74:77], v[138:141], v[208:211], v[74:77]
	v_mfma_f32_16x16x32_bf16 v[130:133], v[134:137], v[180:183], v[130:133]
	v_mfma_f32_16x16x32_bf16 v[126:129], v[142:145], v[180:183], v[126:129]
	v_mfma_f32_16x16x32_bf16 v[110:113], v[134:137], v[196:199], v[110:113]
	v_mfma_f32_16x16x32_bf16 v[106:109], v[142:145], v[196:199], v[106:109]
	v_mfma_f32_16x16x32_bf16 v[94:97], v[134:137], v[204:207], v[94:97]
	v_mfma_f32_16x16x32_bf16 v[90:93], v[142:145], v[204:207], v[90:93]
	v_mfma_f32_16x16x32_bf16 v[78:81], v[134:137], v[212:215], v[78:81]
	v_mfma_f32_16x16x32_bf16 v[74:77], v[142:145], v[212:215], v[74:77]
	v_mfma_f32_16x16x32_bf16 v[118:121], v[146:149], v[176:179], v[118:121]
	v_mfma_f32_16x16x32_bf16 v[114:117], v[154:157], v[176:179], v[114:117]
	v_mfma_f32_16x16x32_bf16 v[102:105], v[146:149], v[192:195], v[102:105]
	v_mfma_f32_16x16x32_bf16 v[98:101], v[154:157], v[192:195], v[98:101]
	v_mfma_f32_16x16x32_bf16 v[86:89], v[146:149], v[200:203], v[86:89]
	v_mfma_f32_16x16x32_bf16 v[82:85], v[154:157], v[200:203], v[82:85]
	v_mfma_f32_16x16x32_bf16 v[70:73], v[146:149], v[208:211], v[70:73]
	v_mfma_f32_16x16x32_bf16 v[66:69], v[154:157], v[208:211], v[66:69]
	v_mfma_f32_16x16x32_bf16 v[118:121], v[150:153], v[180:183], v[118:121]
	v_mfma_f32_16x16x32_bf16 v[114:117], v[172:175], v[180:183], v[114:117]
	v_mfma_f32_16x16x32_bf16 v[102:105], v[150:153], v[196:199], v[102:105]
	v_mfma_f32_16x16x32_bf16 v[98:101], v[172:175], v[196:199], v[98:101]
	v_mfma_f32_16x16x32_bf16 v[86:89], v[150:153], v[204:207], v[86:89]
	v_mfma_f32_16x16x32_bf16 v[82:85], v[172:175], v[204:207], v[82:85]
	v_mfma_f32_16x16x32_bf16 v[70:73], v[150:153], v[212:215], v[70:73]
	v_mfma_f32_16x16x32_bf16 v[66:69], v[172:175], v[212:215], v[66:69]
	s_setprio 0
	s_barrier
	s_add_i32 s55, s55, s56
	v_lshl_add_u64 v[184:185], s[6:7], 0, v[162:163]
	s_mov_b32 m0, s55
	ds_read_b128 v[176:179], v190 offset:16384
	ds_read_b128 v[180:183], v190 offset:17408
	ds_read_b128 v[192:195], v190 offset:18432
	ds_read_b128 v[196:199], v190 offset:19456
	ds_read_b128 v[200:203], v190 offset:20480
	ds_read_b128 v[204:207], v190 offset:21504
	ds_read_b128 v[208:211], v190 offset:22528
	ds_read_b128 v[212:215], v190 offset:23552
	global_load_lds_dwordx4 v[184:185], off
	s_add_i32 m0, s55, 0x2000
	v_lshl_add_u64 v[216:217], s[6:7], 0, v[158:159]
	s_add_u32 s6, s6, s8
	s_addc_u32 s7, s7, 0
	s_add_i32 s24, s24, s56
	global_load_lds_dwordx4 v[216:217], off
	v_lshl_add_u64 v[218:219], s[6:7], 0, v[162:163]
	s_mov_b32 m0, s24
	v_lshl_add_u64 v[220:221], s[6:7], 0, v[158:159]
	global_load_lds_dwordx4 v[218:219], off
	s_add_i32 m0, s24, 0x2000
	v_lshl_add_u64 v[222:223], s[52:53], 0, v[164:165]
	global_load_lds_dwordx4 v[220:221], off
	s_mov_b32 m0, s57
	v_lshl_add_u64 v[224:225], s[52:53], 0, v[160:161]
	global_load_lds_dwordx4 v[222:223], off
	s_mov_b32 m0, s58
	s_nop 0
	global_load_lds_dwordx4 v[224:225], off
	s_waitcnt vmcnt(8)
	s_waitcnt lgkmcnt(0)
	s_barrier
	s_setprio 1
	s_waitcnt lgkmcnt(0)
	v_mfma_f32_16x16x32_bf16 v[62:65], v[122:125], v[176:179], v[62:65]
	v_mfma_f32_16x16x32_bf16 v[58:61], v[138:141], v[176:179], v[58:61]
	v_mfma_f32_16x16x32_bf16 v[46:49], v[122:125], v[192:195], v[46:49]
	v_mfma_f32_16x16x32_bf16 v[42:45], v[138:141], v[192:195], v[42:45]
	v_mfma_f32_16x16x32_bf16 v[30:33], v[122:125], v[200:203], v[30:33]
	v_mfma_f32_16x16x32_bf16 v[26:29], v[138:141], v[200:203], v[26:29]
	v_mfma_f32_16x16x32_bf16 v[14:17], v[122:125], v[208:211], v[14:17]
	v_mfma_f32_16x16x32_bf16 v[10:13], v[138:141], v[208:211], v[10:13]
	v_mfma_f32_16x16x32_bf16 v[62:65], v[134:137], v[180:183], v[62:65]
	v_mfma_f32_16x16x32_bf16 v[58:61], v[142:145], v[180:183], v[58:61]
	v_mfma_f32_16x16x32_bf16 v[46:49], v[134:137], v[196:199], v[46:49]
	v_mfma_f32_16x16x32_bf16 v[42:45], v[142:145], v[196:199], v[42:45]
	v_mfma_f32_16x16x32_bf16 v[30:33], v[134:137], v[204:207], v[30:33]
	v_mfma_f32_16x16x32_bf16 v[26:29], v[142:145], v[204:207], v[26:29]
	v_mfma_f32_16x16x32_bf16 v[14:17], v[134:137], v[212:215], v[14:17]
	v_mfma_f32_16x16x32_bf16 v[10:13], v[142:145], v[212:215], v[10:13]
	v_mfma_f32_16x16x32_bf16 v[54:57], v[146:149], v[176:179], v[54:57]
	v_mfma_f32_16x16x32_bf16 v[50:53], v[154:157], v[176:179], v[50:53]
	v_mfma_f32_16x16x32_bf16 v[38:41], v[146:149], v[192:195], v[38:41]
	v_mfma_f32_16x16x32_bf16 v[34:37], v[154:157], v[192:195], v[34:37]
	v_mfma_f32_16x16x32_bf16 v[22:25], v[146:149], v[200:203], v[22:25]
	v_mfma_f32_16x16x32_bf16 v[18:21], v[154:157], v[200:203], v[18:21]
	v_mfma_f32_16x16x32_bf16 v[6:9], v[146:149], v[208:211], v[6:9]
	v_mfma_f32_16x16x32_bf16 v[2:5], v[154:157], v[208:211], v[2:5]
	v_mfma_f32_16x16x32_bf16 v[54:57], v[150:153], v[180:183], v[54:57]
	v_mfma_f32_16x16x32_bf16 v[50:53], v[172:175], v[180:183], v[50:53]
	v_mfma_f32_16x16x32_bf16 v[38:41], v[150:153], v[196:199], v[38:41]
	v_mfma_f32_16x16x32_bf16 v[34:37], v[172:175], v[196:199], v[34:37]
	v_mfma_f32_16x16x32_bf16 v[22:25], v[150:153], v[204:207], v[22:25]
	v_mfma_f32_16x16x32_bf16 v[18:21], v[172:175], v[204:207], v[18:21]
	v_mfma_f32_16x16x32_bf16 v[6:9], v[150:153], v[212:215], v[6:9]
	v_mfma_f32_16x16x32_bf16 v[2:5], v[172:175], v[212:215], v[2:5]
	s_setprio 0
	s_barrier
	s_add_i32 s24, 0, 0x18000
	s_add_i32 s55, 0, 0x1c000
	v_add_u32_e32 v142, s24, v188
	v_add_u32_e32 v171, s55, v188
	ds_read_b128 v[122:125], v142
	ds_read_b128 v[134:137], v142 offset:1024
	ds_read_b128 v[138:141], v142 offset:2048
	ds_read_b128 v[142:145], v142 offset:3072
	ds_read_b128 v[146:149], v171
	ds_read_b128 v[150:153], v171 offset:1024
	ds_read_b128 v[154:157], v171 offset:2048
	ds_read_b128 v[172:175], v171 offset:3072
	s_add_u32 s6, s52, s8
	s_addc_u32 s7, s53, 0
	s_mov_b32 m0, s59
	v_lshl_add_u64 v[226:227], s[6:7], 0, v[164:165]
	ds_read_b128 v[176:179], v190 offset:32768
	ds_read_b128 v[180:183], v190 offset:33792
	ds_read_b128 v[192:195], v190 offset:34816
	ds_read_b128 v[196:199], v190 offset:35840
	ds_read_b128 v[200:203], v190 offset:36864
	ds_read_b128 v[204:207], v190 offset:37888
	ds_read_b128 v[208:211], v190 offset:38912
	ds_read_b128 v[212:215], v190 offset:39936
	global_load_lds_dwordx4 v[226:227], off
	v_lshl_add_u64 v[226:227], s[6:7], 0, v[160:161]
	s_mov_b32 m0, s60
	s_nop 0
	global_load_lds_dwordx4 v[226:227], off
	s_waitcnt vmcnt(8)
	s_waitcnt lgkmcnt(0)
	s_barrier
	s_setprio 1
	s_waitcnt lgkmcnt(0)
	v_mfma_f32_16x16x32_bf16 v[130:133], v[122:125], v[176:179], v[130:133]
	v_mfma_f32_16x16x32_bf16 v[126:129], v[138:141], v[176:179], v[126:129]
	v_mfma_f32_16x16x32_bf16 v[110:113], v[122:125], v[192:195], v[110:113]
	v_mfma_f32_16x16x32_bf16 v[106:109], v[138:141], v[192:195], v[106:109]
	v_mfma_f32_16x16x32_bf16 v[94:97], v[122:125], v[200:203], v[94:97]
	v_mfma_f32_16x16x32_bf16 v[90:93], v[138:141], v[200:203], v[90:93]
	v_mfma_f32_16x16x32_bf16 v[78:81], v[122:125], v[208:211], v[78:81]
	v_mfma_f32_16x16x32_bf16 v[74:77], v[138:141], v[208:211], v[74:77]
	v_mfma_f32_16x16x32_bf16 v[130:133], v[134:137], v[180:183], v[130:133]
	v_mfma_f32_16x16x32_bf16 v[126:129], v[142:145], v[180:183], v[126:129]
	v_mfma_f32_16x16x32_bf16 v[110:113], v[134:137], v[196:199], v[110:113]
	v_mfma_f32_16x16x32_bf16 v[106:109], v[142:145], v[196:199], v[106:109]
	v_mfma_f32_16x16x32_bf16 v[94:97], v[134:137], v[204:207], v[94:97]
	v_mfma_f32_16x16x32_bf16 v[90:93], v[142:145], v[204:207], v[90:93]
	v_mfma_f32_16x16x32_bf16 v[78:81], v[134:137], v[212:215], v[78:81]
	v_mfma_f32_16x16x32_bf16 v[74:77], v[142:145], v[212:215], v[74:77]
	v_mfma_f32_16x16x32_bf16 v[118:121], v[146:149], v[176:179], v[118:121]
	v_mfma_f32_16x16x32_bf16 v[114:117], v[154:157], v[176:179], v[114:117]
	v_mfma_f32_16x16x32_bf16 v[102:105], v[146:149], v[192:195], v[102:105]
	v_mfma_f32_16x16x32_bf16 v[98:101], v[154:157], v[192:195], v[98:101]
	v_mfma_f32_16x16x32_bf16 v[86:89], v[146:149], v[200:203], v[86:89]
	v_mfma_f32_16x16x32_bf16 v[82:85], v[154:157], v[200:203], v[82:85]
	v_mfma_f32_16x16x32_bf16 v[70:73], v[146:149], v[208:211], v[70:73]
	v_mfma_f32_16x16x32_bf16 v[66:69], v[154:157], v[208:211], v[66:69]
	v_mfma_f32_16x16x32_bf16 v[118:121], v[150:153], v[180:183], v[118:121]
	v_mfma_f32_16x16x32_bf16 v[114:117], v[172:175], v[180:183], v[114:117]
	v_mfma_f32_16x16x32_bf16 v[102:105], v[150:153], v[196:199], v[102:105]
	v_mfma_f32_16x16x32_bf16 v[98:101], v[172:175], v[196:199], v[98:101]
	v_mfma_f32_16x16x32_bf16 v[86:89], v[150:153], v[204:207], v[86:89]
	v_mfma_f32_16x16x32_bf16 v[82:85], v[172:175], v[204:207], v[82:85]
	v_mfma_f32_16x16x32_bf16 v[70:73], v[150:153], v[212:215], v[70:73]
	v_mfma_f32_16x16x32_bf16 v[66:69], v[172:175], v[212:215], v[66:69]
	s_setprio 0
	s_barrier
	s_add_i32 s6, s24, s56
	v_lshl_add_u64 v[184:185], v[184:185], 0, s[84:85]
	s_mov_b32 m0, s6
	ds_read_b128 v[176:179], v190 offset:49152
	ds_read_b128 v[180:183], v190 offset:50176
	ds_read_b128 v[192:195], v190 offset:51200
	ds_read_b128 v[196:199], v190 offset:52224
	ds_read_b128 v[200:203], v190 offset:53248
	ds_read_b128 v[204:207], v190 offset:54272
	ds_read_b128 v[208:211], v190 offset:55296
	ds_read_b128 v[212:215], v190 offset:56320
	global_load_lds_dwordx4 v[184:185], off
	v_lshl_add_u64 v[184:185], v[216:217], 0, s[84:85]
	s_add_i32 m0, s6, 0x2000
	s_add_i32 s6, s55, s56
	global_load_lds_dwordx4 v[184:185], off
	v_lshl_add_u64 v[184:185], v[218:219], 0, s[84:85]
	s_mov_b32 m0, s6
	s_nop 0
	global_load_lds_dwordx4 v[184:185], off
	v_lshl_add_u64 v[184:185], v[220:221], 0, s[84:85]
	s_add_i32 m0, s6, 0x2000
	s_nop 0
	global_load_lds_dwordx4 v[184:185], off
	v_lshl_add_u64 v[184:185], v[222:223], 0, s[84:85]
	s_mov_b32 m0, s65
	s_nop 0
	global_load_lds_dwordx4 v[184:185], off
	v_lshl_add_u64 v[184:185], v[224:225], 0, s[84:85]
	s_mov_b32 m0, s66
	s_nop 0
	global_load_lds_dwordx4 v[184:185], off
	s_waitcnt vmcnt(8)
	s_waitcnt lgkmcnt(0)
	s_barrier
	s_setprio 1
	s_waitcnt lgkmcnt(0)
	v_mfma_f32_16x16x32_bf16 v[62:65], v[122:125], v[176:179], v[62:65]
	v_mfma_f32_16x16x32_bf16 v[58:61], v[138:141], v[176:179], v[58:61]
	v_mfma_f32_16x16x32_bf16 v[46:49], v[122:125], v[192:195], v[46:49]
	v_mfma_f32_16x16x32_bf16 v[42:45], v[138:141], v[192:195], v[42:45]
	v_mfma_f32_16x16x32_bf16 v[30:33], v[122:125], v[200:203], v[30:33]
	v_mfma_f32_16x16x32_bf16 v[26:29], v[138:141], v[200:203], v[26:29]
	v_mfma_f32_16x16x32_bf16 v[14:17], v[122:125], v[208:211], v[14:17]
	v_mfma_f32_16x16x32_bf16 v[10:13], v[138:141], v[208:211], v[10:13]
	v_mfma_f32_16x16x32_bf16 v[62:65], v[134:137], v[180:183], v[62:65]
	v_mfma_f32_16x16x32_bf16 v[58:61], v[142:145], v[180:183], v[58:61]
	v_mfma_f32_16x16x32_bf16 v[46:49], v[134:137], v[196:199], v[46:49]
	v_mfma_f32_16x16x32_bf16 v[42:45], v[142:145], v[196:199], v[42:45]
	v_mfma_f32_16x16x32_bf16 v[30:33], v[134:137], v[204:207], v[30:33]
	v_mfma_f32_16x16x32_bf16 v[26:29], v[142:145], v[204:207], v[26:29]
	v_mfma_f32_16x16x32_bf16 v[14:17], v[134:137], v[212:215], v[14:17]
	v_mfma_f32_16x16x32_bf16 v[10:13], v[142:145], v[212:215], v[10:13]
	v_mfma_f32_16x16x32_bf16 v[54:57], v[146:149], v[176:179], v[54:57]
	v_mfma_f32_16x16x32_bf16 v[50:53], v[154:157], v[176:179], v[50:53]
	v_mfma_f32_16x16x32_bf16 v[38:41], v[146:149], v[192:195], v[38:41]
	v_mfma_f32_16x16x32_bf16 v[34:37], v[154:157], v[192:195], v[34:37]
	v_mfma_f32_16x16x32_bf16 v[22:25], v[146:149], v[200:203], v[22:25]
	v_mfma_f32_16x16x32_bf16 v[18:21], v[154:157], v[200:203], v[18:21]
	v_mfma_f32_16x16x32_bf16 v[6:9], v[146:149], v[208:211], v[6:9]
	v_mfma_f32_16x16x32_bf16 v[2:5], v[154:157], v[208:211], v[2:5]
	v_mfma_f32_16x16x32_bf16 v[54:57], v[150:153], v[180:183], v[54:57]
	v_mfma_f32_16x16x32_bf16 v[50:53], v[172:175], v[180:183], v[50:53]
	v_mfma_f32_16x16x32_bf16 v[38:41], v[150:153], v[196:199], v[38:41]
	v_mfma_f32_16x16x32_bf16 v[34:37], v[172:175], v[196:199], v[34:37]
	v_mfma_f32_16x16x32_bf16 v[22:25], v[150:153], v[204:207], v[22:25]
	v_mfma_f32_16x16x32_bf16 v[18:21], v[172:175], v[204:207], v[18:21]
	v_mfma_f32_16x16x32_bf16 v[6:9], v[150:153], v[212:215], v[6:9]
	v_mfma_f32_16x16x32_bf16 v[2:5], v[172:175], v[212:215], v[2:5]
	s_setprio 0
	s_barrier
	s_add_u32 s50, s50, 0x100
	s_addc_u32 s51, s51, 0
	s_add_u32 s37, s37, 0x100
	s_addc_u32 s54, s54, 0
	s_cmp_ge_u32 s25, s62
	s_mov_b32 s24, s25
	s_cbranch_scc0 .LBB0_763
	s_and_b64 vcc, exec, s[44:45]
	s_cbranch_vccz .LBB0_766
	s_barrier
